# rope tables fetched by LDS-DMA once per phase (flag in s101) instead of per unit; chunk-0 loads after the DMA block; per-chunk vmcnt waits dropped
# speedup vs baseline: 1.0042x; 1.0006x over previous
; #define PG8_STAGE(bufoff, gbase, voff) do { _Pragma("unroll") for (int _i = 0; _i < 2; ++_i) \
;         __builtin_amdgcn_global_load_lds((const unsigned*)((const char*)(gbase) + (voff)[_i]), (PG8_LAS unsigned*)(lds + (bufoff) + ldsw + _i * 8192), 16, 0, 0); } while (0)
; #define PG8_WAIT_V(n) asm volatile("s_waitcnt vmcnt(" #n ")" ::: "memory")
; #define PG8_BAR __builtin_amdgcn_s_barrier()
;     ...
;     const char* cA = (const char*)g.A + (size_t)cur.pm * tstep; const char* cB = (const char*)g.Bt + (size_t)cur.pn * tstep;
;     S.a_ready(cur);
;     if constexpr (SP2) {
;         PG8_STAGE(PG8_SB(0, 0), cB, voffB); PG8_STAGE(PG8_SB(0, 1), cB + hstep, voffB); PG8_STAGE(PG8_SA(0, 0), cA, voffA); PG8_STAGE(PG8_SA(0, 1), cA + hstep, voffA);
;         if (wr == 1) PG8_BAR;
;         PG8_WAIT_V(2); PG8_BAR;
;         PG8_STAGE(PG8_SB(1, 0), cB + kstep, voffB); PG8_STAGE(PG8_SA(1, 0), cA + kstep, voffA); PG8_STAGE(PG8_SB(1, 1), cB + hstep + kstep, voffB);
;         PG8_WAIT_V(6); PG8_BAR;
;     } else {
;         PG8_STAGE(PG8_SB(0, 0), cB, voffB); PG8_STAGE(PG8_SA(0, 0), cA, voffA); PG8_STAGE(PG8_SB(0, 1), cB + hstep, voffB); PG8_STAGE(PG8_SA(0, 1), cA + hstep, voffA);
;         if (wr == 1) PG8_BAR;
;         PG8_WAIT_V(4); PG8_BAR;
;         PG8_STAGE(PG8_SB(1, 0), cB + kstep, voffB); PG8_STAGE(PG8_SA(1, 0), cA + kstep, voffA); PG8_STAGE(PG8_SB(1, 1), cB + hstep + kstep, voffB);
;         PG8_WAIT_V(6); PG8_BAR;
.LBB0_747:
	v_and_b32_e32 v3, 15, v10
	v_bfe_u32 v15, v10, 4, 2
	v_readlane_b32 s68, v254, 47
	v_lshlrev_b32_e32 v20, 3, v15
	v_lshlrev_b32_e32 v15, 4, v15
	v_lshlrev_b32_e32 v21, 2, v3
	v_mov_b32_e32 v143, v201
	v_readlane_b32 s69, v254, 48
	s_mov_b32 s101, 0
	s_and_b32 s14, s12, 3
	s_lshl_b32 s20, s9, 6
	v_lshl_or_b32 v15, v3, 6, v15
	s_lshl_b32 s9, s9, 13
	v_and_b32_e32 v22, 32, v21
	s_add_i32 m0, s1, 0x18000
	v_lshl_add_u64 v[4:5], v[4:5], 0, s[66:67]
	v_lshl_add_u64 v[16:17], s[68:69], 0, v[142:143]
	v_mov_b32_e32 v139, v201
	v_bitop3_b32 v23, v15, s9, v22 bitop3:0xde
	s_lshl_b32 s9, s14, 12
	s_waitcnt vmcnt(2)
	s_barrier
	global_load_lds_dwordx4 v[4:5], off
	v_lshl_add_u64 v[4:5], v[6:7], 0, s[66:67]
	s_add_i32 m0, s1, 0x1a000
	s_add_i32 s21, s1, 0x8000
	s_add_i32 s23, s1, 0xa000
	v_lshl_add_u64 v[18:19], s[68:69], 0, v[138:139]
	global_load_lds_dwordx4 v[4:5], off
	v_lshl_add_u64 v[4:5], v[16:17], 0, s[66:67]
	s_mov_b32 m0, s21
	s_add_u32 s12, s76, 0x80080
	global_load_lds_dwordx4 v[4:5], off
	v_lshl_add_u64 v[4:5], v[18:19], 0, s[66:67]
	s_mov_b32 m0, s23
	s_addc_u32 s13, s77, 0
	global_load_lds_dwordx4 v[4:5], off
	s_add_i32 m0, s1, 0x1c000
	v_lshl_add_u64 v[4:5], s[12:13], 0, v[140:141]
	global_load_lds_dwordx4 v[4:5], off
	v_lshl_add_u64 v[4:5], s[12:13], 0, v[136:137]
	s_add_i32 m0, s1, 0x1e000
	s_cmpk_lt_u32 s8, 0x100
	global_load_lds_dwordx4 v[4:5], off
	v_lshrrev_b32_e32 v5, 3, v10
	v_and_b32_e32 v144, 4, v5
	v_lshlrev_b32_e32 v5, 15, v13
	v_and_b32_e32 v5, 0xffff0000, v5
	v_lshl_add_u32 v5, v12, 12, v5
	v_and_b32_e32 v7, 1, v13
	s_cselect_b64 s[12:13], -1, 0
	s_and_b32 s15, s8, 0xffffff00
	v_lshl_or_b32 v5, v7, 6, v5
	s_cmp_lg_u32 s14, 0
	v_and_b32_e32 v4, 8, v20
	v_readlane_b32 s24, v254, 7
	v_lshl_add_u32 v150, v14, 1, v5
	v_lshlrev_b32_e32 v5, 15, v8
	v_bitop3_b32 v145, v15, s9, v22 bitop3:0xde
	s_cselect_b64 s[8:9], -1, 0
	v_lshl_or_b32 v6, s14, 5, v20
	v_lshlrev_b32_e32 v200, 2, v4
	v_readlane_b32 s25, v254, 8
	s_add_i32 s14, s15, 0
	v_and_b32_e32 v5, 0xffff0000, v5
	s_waitcnt vmcnt(6)
	v_lshl_add_u64 v[146:147], s[24:25], 0, v[200:201]
	v_readlane_b32 s24, v254, 9
	s_add_i32 s14, s14, 0x23c00
	v_lshl_add_u32 v5, v9, 12, v5
	v_and_b32_e32 v7, 1, v8
	v_readlane_b32 s25, v254, 10
	v_add_u32_e32 v174, s14, v21
	v_lshl_or_b32 v5, v7, 6, v5
	s_xor_b64 s[14:15], s[8:9], -1
	v_readlane_b32 s8, v254, 43
	s_mov_b32 s42, 0
	v_lshl_add_u64 v[148:149], s[24:25], 0, v[200:201]
	v_mov_b32_e32 v151, v201
	v_lshl_add_u32 v152, v11, 1, v5
	v_mov_b32_e32 v153, v201
	v_add_u32_e32 v175, 0, v23
	v_lshlrev_b32_e32 v154, 1, v4
	v_lshlrev_b32_e32 v156, 1, v6
	s_mov_b32 s44, s8
	v_readlane_b32 s52, v254, 42
	s_barrier
	v_readlane_b32 s9, v254, 44
	s_branch .LBB0_750

; #define PG8_G __attribute__((address_space(1)))
;     __device__ __forceinline__ void operator()(const f32x4 (&acc)[2][2][4][2], const Unit& u, int wr, int wc, int fr, int fq, int ui) const {
;     ...
;             const int hh = fq >> 1, i0 = 8 * (fq & 1);
; #pragma unroll
;             for (int ai = 0; ai < 2; ++ai)
; #pragma unroll
;                 for (int m = 0; m < 4; ++m) { const int row = row0 + ai * HALF + m * 16, b = row >> 12, s = row & 4095, sp = ((s & ((1 << sh) - 1)) << (12 - sh)) + (s >> sh);
;                     const f32x4 c0 = *(const PG8_G f32x4*)(cosT + (size_t)row * 16 + i0), c1 = *(const PG8_G f32x4*)(cosT + (size_t)row * 16 + i0 + 4);
;                     const f32x4 s0 = *(const PG8_G f32x4*)(sinT + (size_t)row * 16 + i0), s1 = *(const PG8_G f32x4*)(sinT + (size_t)row * 16 + i0 + 4);
.LBB0_759:
	v_ashrrev_i32_e32 v167, 31, v166
	v_lshlrev_b64 v[132:133], 6, v[166:167]
	v_lshl_add_u64 v[134:135], v[148:149], 0, v[132:133]
	v_lshl_add_u64 v[132:133], v[146:147], 0, v[132:133]
	s_mov_b64 s[98:99], 0x2000
	v_lshl_add_u64 v[236:237], v[134:135], 0, s[98:99]
	v_lshl_add_u64 v[238:239], v[132:133], 0, s[98:99]
	v_readfirstlane_b32 s100, v0
	s_nop 3
	s_lshr_b32 s100, s100, 8
	s_xor_b32 s100, s100, 1
	s_mul_i32 s100, s100, 0x3c00
	s_add_i32 s100, s100, 0x20400
	v_and_b32_e32 v240, 31, v0
	v_lshl_add_u32 v240, v240, 4, s100
	s_cmp_eq_u32 s101, 0
	s_cbranch_scc0 .Lrope_tab_ready
	s_mov_b64 s[98:99], exec
	s_mov_b32 exec_hi, 0
	s_mov_b32 exec_lo, -1
	s_sub_i32 m0, s100, 1024
	s_nop 0
	global_load_lds_dwordx4 v[134:135], off offset:1024
	s_sub_i32 m0, s100, 528
	s_nop 0
	global_load_lds_dwordx4 v[134:135], off offset:1040
	s_add_i32 m0, s100, 0
	s_nop 0
	global_load_lds_dwordx4 v[132:133], off offset:1024
	s_add_i32 m0, s100, 496
	s_nop 0
	global_load_lds_dwordx4 v[132:133], off offset:1040
	s_add_i32 m0, s100, 0
	s_nop 0
	global_load_lds_dwordx4 v[134:135], off offset:2048
	s_add_i32 m0, s100, 496
	s_nop 0
	global_load_lds_dwordx4 v[134:135], off offset:2064
	s_add_i32 m0, s100, 1024
	s_nop 0
	global_load_lds_dwordx4 v[132:133], off offset:2048
	s_add_i32 m0, s100, 1520
	s_nop 0
	global_load_lds_dwordx4 v[132:133], off offset:2064
	s_add_i32 m0, s100, 1024
	s_nop 0
	global_load_lds_dwordx4 v[134:135], off offset:3072
	s_add_i32 m0, s100, 1520
	s_nop 0
	global_load_lds_dwordx4 v[134:135], off offset:3088
	s_add_i32 m0, s100, 2048
	s_nop 0
	global_load_lds_dwordx4 v[132:133], off offset:3072
	s_add_i32 m0, s100, 2544
	s_nop 0
	global_load_lds_dwordx4 v[132:133], off offset:3088
	s_add_i32 m0, s100, 6144
	s_nop 0
	global_load_lds_dwordx4 v[236:237], off
	s_add_i32 m0, s100, 6640
	s_nop 0
	global_load_lds_dwordx4 v[236:237], off offset:16
	s_add_i32 m0, s100, 7168
	s_nop 0
	global_load_lds_dwordx4 v[238:239], off
	s_add_i32 m0, s100, 7664
	s_nop 0
	global_load_lds_dwordx4 v[238:239], off offset:16
	s_add_i32 m0, s100, 7168
	s_nop 0
	global_load_lds_dwordx4 v[236:237], off offset:1024
	s_add_i32 m0, s100, 7664
	s_nop 0
	global_load_lds_dwordx4 v[236:237], off offset:1040
	s_add_i32 m0, s100, 8192
	s_nop 0
	global_load_lds_dwordx4 v[238:239], off offset:1024
	s_add_i32 m0, s100, 8688
	s_nop 0
	global_load_lds_dwordx4 v[238:239], off offset:1040
	s_add_i32 m0, s100, 8192
	s_nop 0
	global_load_lds_dwordx4 v[236:237], off offset:2048
	s_add_i32 m0, s100, 8688
	s_nop 0
	global_load_lds_dwordx4 v[236:237], off offset:2064
	s_add_i32 m0, s100, 9216
	s_nop 0
	global_load_lds_dwordx4 v[238:239], off offset:2048
	s_add_i32 m0, s100, 9712
	s_nop 0
	global_load_lds_dwordx4 v[238:239], off offset:2064
	s_add_i32 m0, s100, 9216
	s_nop 0
	global_load_lds_dwordx4 v[236:237], off offset:3072
	s_add_i32 m0, s100, 9712
	s_nop 0
	global_load_lds_dwordx4 v[236:237], off offset:3088
	s_add_i32 m0, s100, 10240
	s_nop 0
	global_load_lds_dwordx4 v[238:239], off offset:3072
	s_add_i32 m0, s100, 10736
	s_nop 0
	global_load_lds_dwordx4 v[238:239], off offset:3088
	s_mov_b64 exec, s[98:99]
	s_mov_b32 s101, 1
.Lrope_tab_ready:
	global_load_dwordx4 v[178:181], v[134:135], off
	global_load_dwordx4 v[182:185], v[134:135], off offset:16
	global_load_dwordx4 v[186:189], v[132:133], off
	global_load_dwordx4 v[190:193], v[132:133], off offset:16
	s_barrier
	s_sub_i32 s52, 12, s44
	s_ashr_i32 s54, s25, 12
	v_mov_b32_e32 v133, s69
	v_or_b32_e32 v132, s68, v144
	v_lshlrev_b32_e32 v134, s52, v166
	s_ashr_i32 s55, s54, 31
	v_and_b32_e32 v167, 0xfff, v134
	v_lshl_add_u64 v[134:135], v[132:133], 0, s[54:55]
	v_lshlrev_b64 v[134:135], 20, v[134:135]
	v_or_b32_e32 v172, 16, v166
	s_waitcnt lgkmcnt(0)
	v_pk_mul_f32 v[194:195], v[130:131], v[164:165] op_sel_hi:[1,0]
	v_pk_mul_f32 v[196:197], v[128:129], v[164:165] op_sel_hi:[1,0]
	v_pk_mul_f32 v[208:209], v[122:123], v[164:165] op_sel_hi:[1,0]
	v_pk_mul_f32 v[210:211], v[120:121], v[164:165] op_sel_hi:[1,0]
	v_pk_mul_f32 v[212:213], v[114:115], v[164:165] op_sel_hi:[1,0]
	v_pk_mul_f32 v[214:215], v[112:113], v[164:165] op_sel_hi:[1,0]
	v_add_lshl_u32 v200, v167, v157, 8
	v_lshl_add_u64 v[134:135], s[50:51], 0, v[134:135]
	v_pk_mul_f32 v[198:199], v[126:127], v[164:165] op_sel_hi:[1,0]
	v_pk_mul_f32 v[206:207], v[124:125], v[164:165] op_sel_hi:[1,0]
	v_mov_b32_e32 v155, v201
	v_ashrrev_i32_e32 v173, 31, v172
	v_lshl_add_u64 v[220:221], v[134:135], 0, v[200:201]
	v_lshlrev_b64 v[216:217], 6, v[172:173]
	v_lshl_add_u64 v[220:221], v[220:221], 0, v[154:155]
	v_lshl_add_u64 v[218:219], v[148:149], 0, v[216:217]
	s_movk_i32 s48, 0xfdf
	v_bitop3_b32 v167, v166, s48, 16 bitop3:0xc8
	v_lshlrev_b32_e32 v169, s52, v172
	v_lshrrev_b32_e32 v167, s44, v167
	v_and_b32_e32 v169, 0xfff, v169
	v_add_lshl_u32 v200, v169, v167, 8
	s_movk_i32 s48, 0xfef
	v_bitop3_b32 v167, v166, s48, 32 bitop3:0xc8
	v_lshrrev_b32_e32 v167, s44, v167
	v_ashrrev_i32_e32 v171, 31, v170
	s_waitcnt vmcnt(0)
; #define PG8_G __attribute__((address_space(1)))
; __device__ __forceinline__ u32x4 pack8bf(const f32x4 a, const f32x4 b) { u32x4 w; w.x = cvt_pk_bf16(a[0], a[1]); w.y = cvt_pk_bf16(a[2], a[3]); w.z = cvt_pk_bf16(b[0], b[1]); w.w = cvt_pk_bf16(b[2], b[3]); return w; }
;     __device__ __forceinline__ void operator()(const f32x4 (&acc)[2][2][4][2], const Unit& u, int wr, int wc, int fr, int fq, int ui) const {
;     ...
;             const int hh = fq >> 1, i0 = 8 * (fq & 1);
; #pragma unroll
;             for (int ai = 0; ai < 2; ++ai)
; #pragma unroll
;                 for (int m = 0; m < 4; ++m) { const int row = row0 + ai * HALF + m * 16, b = row >> 12, s = row & 4095, sp = ((s & ((1 << sh) - 1)) << (12 - sh)) + (s >> sh);
;                     const f32x4 c0 = *(const PG8_G f32x4*)(cosT + (size_t)row * 16 + i0), c1 = *(const PG8_G f32x4*)(cosT + (size_t)row * 16 + i0 + 4);
;                     const f32x4 s0 = *(const PG8_G f32x4*)(sinT + (size_t)row * 16 + i0), s1 = *(const PG8_G f32x4*)(sinT + (size_t)row * 16 + i0 + 4);
;                     const f32x4 x1a = acc[ai][0][m][0] * r[ai][m], x1b = acc[ai][0][m][1] * r[ai][m], x2a = acc[ai][1][m][0] * r[ai][m], x2b = acc[ai][1][m][1] * r[ai][m];
;                     const f32x4 y1a = x1a * c0 - x2a * s0, y1b = x1b * c1 - x2b * s1, y2a = x2a * c0 + x1a * s0, y2b = x2b * c1 + x1b * s1;
;                     bf16_t* dst = O + ((plane + hh * 4 + b) * 4096 + sp) * 128 + i0;
;                     *(PG8_G u32x4*)dst = pack8bf(y1a, y1b); *(PG8_G u32x4*)(dst + 16) = pack8bf(y2a, y2b); }
	v_pk_mul_f32 v[222:223], v[208:209], v[180:181]
	v_pk_mul_f32 v[224:225], v[210:211], v[178:179]
	v_pk_mul_f32 v[232:233], v[212:213], v[184:185]
	v_pk_mul_f32 v[234:235], v[214:215], v[182:183]
	v_pk_mul_f32 v[180:181], v[194:195], v[180:181]
	v_pk_mul_f32 v[178:179], v[196:197], v[178:179]
	v_pk_mul_f32 v[184:185], v[198:199], v[184:185]
	v_pk_mul_f32 v[182:183], v[206:207], v[182:183]
	v_pk_fma_f32 v[194:195], v[194:195], v[188:189], v[222:223] neg_lo:[0,0,1] neg_hi:[0,0,1]
	v_pk_fma_f32 v[196:197], v[196:197], v[186:187], v[224:225] neg_lo:[0,0,1] neg_hi:[0,0,1]
	v_pk_fma_f32 v[198:199], v[198:199], v[192:193], v[232:233] neg_lo:[0,0,1] neg_hi:[0,0,1]
	v_pk_fma_f32 v[206:207], v[206:207], v[190:191], v[234:235] neg_lo:[0,0,1] neg_hi:[0,0,1]
	v_pk_fma_f32 v[188:189], v[208:209], v[188:189], v[180:181]
	v_pk_fma_f32 v[186:187], v[210:211], v[186:187], v[178:179]
	v_cvt_pk_bf16_f32 v178, v196, v197
	v_cvt_pk_bf16_f32 v179, v194, v195
	v_cvt_pk_bf16_f32 v180, v206, v207
	v_cvt_pk_bf16_f32 v181, v198, v199
	v_pk_fma_f32 v[184:185], v[212:213], v[192:193], v[184:185]
	v_pk_fma_f32 v[182:183], v[214:215], v[190:191], v[182:183]
	v_mov_b32_e32 v112, v178
	v_mov_b32_e32 v113, v179
	v_mov_b32_e32 v114, v180
	v_mov_b32_e32 v115, v181
	v_mov_b32_e32 v124, v220
	v_mov_b32_e32 v125, v221
	v_lshl_add_u64 v[190:191], v[146:147], 0, v[216:217]
	v_mov_b32_e32 v196, v165
	v_cvt_pk_bf16_f32 v178, v186, v187
	v_cvt_pk_bf16_f32 v179, v188, v189
	v_cvt_pk_bf16_f32 v180, v182, v183
	v_cvt_pk_bf16_f32 v181, v184, v185
	v_mov_b32_e32 v120, v178
	v_mov_b32_e32 v121, v179
	v_mov_b32_e32 v122, v180
	v_mov_b32_e32 v123, v181
	ds_read_b128 v[178:181], v240
	ds_read_b128 v[182:185], v240 offset:512
	ds_read_b128 v[186:189], v240 offset:1024
	ds_read_b128 v[190:193], v240 offset:1536
	v_or_b32_e32 v194, 32, v166
	v_pk_mul_f32 v[172:173], v[118:119], v[196:197] op_sel_hi:[1,0]
	v_pk_mul_f32 v[198:199], v[116:117], v[196:197] op_sel_hi:[1,0]
	v_pk_mul_f32 v[206:207], v[110:111], v[196:197] op_sel_hi:[1,0]
	v_pk_mul_f32 v[208:209], v[108:109], v[196:197] op_sel_hi:[1,0]
	v_pk_mul_f32 v[210:211], v[106:107], v[196:197] op_sel_hi:[1,0]
	v_pk_mul_f32 v[212:213], v[104:105], v[196:197] op_sel_hi:[1,0]
	v_pk_mul_f32 v[214:215], v[98:99], v[196:197] op_sel_hi:[1,0]
	v_pk_mul_f32 v[196:197], v[96:97], v[196:197] op_sel_hi:[1,0]
	v_ashrrev_i32_e32 v195, 31, v194
	v_lshl_add_u64 v[220:221], v[134:135], 0, v[200:201]
	v_lshlrev_b64 v[216:217], 6, v[194:195]
	v_lshl_add_u64 v[220:221], v[220:221], 0, v[154:155]
	v_lshl_add_u64 v[218:219], v[148:149], 0, v[216:217]
	v_lshlrev_b32_e32 v169, s52, v194
	v_and_b32_e32 v169, 0xfff, v169
	v_add_lshl_u32 v200, v169, v167, 8
	v_bitop3_b32 v167, v166, s17, 48 bitop3:0xc8
	v_lshrrev_b32_e32 v167, s44, v167
	s_waitcnt lgkmcnt(3)
	v_pk_mul_f32 v[222:223], v[210:211], v[180:181]
	v_pk_mul_f32 v[224:225], v[212:213], v[178:179]
	s_waitcnt lgkmcnt(2)
	v_pk_mul_f32 v[232:233], v[214:215], v[184:185]
	v_pk_mul_f32 v[234:235], v[196:197], v[182:183]
	v_pk_mul_f32 v[180:181], v[172:173], v[180:181]
	v_pk_mul_f32 v[178:179], v[198:199], v[178:179]
	v_pk_mul_f32 v[184:185], v[206:207], v[184:185]
	v_pk_mul_f32 v[182:183], v[208:209], v[182:183]
	s_waitcnt lgkmcnt(1)
	v_pk_fma_f32 v[172:173], v[172:173], v[188:189], v[222:223] neg_lo:[0,0,1] neg_hi:[0,0,1]
	v_pk_fma_f32 v[198:199], v[198:199], v[186:187], v[224:225] neg_lo:[0,0,1] neg_hi:[0,0,1]
	s_waitcnt lgkmcnt(0)
	v_pk_fma_f32 v[206:207], v[206:207], v[192:193], v[232:233] neg_lo:[0,0,1] neg_hi:[0,0,1]
	v_pk_fma_f32 v[208:209], v[208:209], v[190:191], v[234:235] neg_lo:[0,0,1] neg_hi:[0,0,1]
	v_pk_fma_f32 v[188:189], v[210:211], v[188:189], v[180:181]
	v_pk_fma_f32 v[186:187], v[212:213], v[186:187], v[178:179]
	v_cvt_pk_bf16_f32 v178, v198, v199
	v_cvt_pk_bf16_f32 v179, v172, v173
	v_cvt_pk_bf16_f32 v180, v208, v209
	v_cvt_pk_bf16_f32 v181, v206, v207
	v_pk_fma_f32 v[184:185], v[214:215], v[192:193], v[184:185]
	v_pk_fma_f32 v[182:183], v[196:197], v[190:191], v[182:183]
	v_mov_b32_e32 v96, v178
	v_mov_b32_e32 v97, v179
	v_mov_b32_e32 v98, v180
	v_mov_b32_e32 v99, v181
	v_mov_b32_e32 v108, v220
	v_mov_b32_e32 v109, v221
	v_lshl_add_u64 v[172:173], v[146:147], 0, v[216:217]
	v_pk_mul_f32 v[196:197], v[102:103], v[162:163] op_sel_hi:[1,0]
	v_cvt_pk_bf16_f32 v178, v186, v187
	v_cvt_pk_bf16_f32 v179, v188, v189
	v_cvt_pk_bf16_f32 v180, v182, v183
	v_cvt_pk_bf16_f32 v181, v184, v185
	v_mov_b32_e32 v104, v178
	v_mov_b32_e32 v105, v179
	v_mov_b32_e32 v106, v180
	v_mov_b32_e32 v107, v181
	ds_read_b128 v[178:181], v240 offset:2048
	ds_read_b128 v[182:185], v240 offset:2560
	ds_read_b128 v[186:189], v240 offset:3072
	ds_read_b128 v[190:193], v240 offset:3584
	v_or_b32_e32 v172, 48, v166
	v_pk_mul_f32 v[198:199], v[100:101], v[162:163] op_sel_hi:[1,0]
	v_pk_mul_f32 v[210:211], v[90:91], v[162:163] op_sel_hi:[1,0]
	v_pk_mul_f32 v[212:213], v[88:89], v[162:163] op_sel_hi:[1,0]
	v_pk_mul_f32 v[214:215], v[82:83], v[162:163] op_sel_hi:[1,0]
	v_pk_mul_f32 v[216:217], v[80:81], v[162:163] op_sel_hi:[1,0]
	v_pk_mul_f32 v[206:207], v[94:95], v[162:163] op_sel_hi:[1,0]
	v_pk_mul_f32 v[208:209], v[92:93], v[162:163] op_sel_hi:[1,0]
	v_ashrrev_i32_e32 v173, 31, v172
	v_lshl_add_u64 v[220:221], v[134:135], 0, v[200:201]
	v_lshlrev_b64 v[194:195], 6, v[172:173]
	v_lshl_add_u64 v[220:221], v[220:221], 0, v[154:155]
	v_lshl_add_u64 v[218:219], v[148:149], 0, v[194:195]
	v_lshlrev_b32_e32 v169, s52, v172
	v_and_b32_e32 v169, 0xfff, v169
	v_add_lshl_u32 v200, v169, v167, 8
	v_lshl_add_u64 v[134:135], v[134:135], 0, v[200:201]
	v_lshl_add_u64 v[134:135], v[134:135], 0, v[154:155]
	v_ashrrev_i32_e32 v169, 31, v168
	v_lshl_add_u64 v[132:133], v[132:133], 0, v[168:169]
	v_lshrrev_b32_e32 v167, s44, v177
	v_lshlrev_b64 v[132:133], 20, v[132:133]
	v_lshl_add_u64 v[132:133], s[50:51], 0, v[132:133]
	s_waitcnt lgkmcnt(3)
; #define PG8_G __attribute__((address_space(1)))
; __device__ __forceinline__ u32x4 pack8bf(const f32x4 a, const f32x4 b) { u32x4 w; w.x = cvt_pk_bf16(a[0], a[1]); w.y = cvt_pk_bf16(a[2], a[3]); w.z = cvt_pk_bf16(b[0], b[1]); w.w = cvt_pk_bf16(b[2], b[3]); return w; }
;     __device__ __forceinline__ void operator()(const f32x4 (&acc)[2][2][4][2], const Unit& u, int wr, int wc, int fr, int fq, int ui) const {
;     ...
;             const int hh = fq >> 1, i0 = 8 * (fq & 1);
; #pragma unroll
;             for (int ai = 0; ai < 2; ++ai)
; #pragma unroll
;                 for (int m = 0; m < 4; ++m) { const int row = row0 + ai * HALF + m * 16, b = row >> 12, s = row & 4095, sp = ((s & ((1 << sh) - 1)) << (12 - sh)) + (s >> sh);
;                     const f32x4 c0 = *(const PG8_G f32x4*)(cosT + (size_t)row * 16 + i0), c1 = *(const PG8_G f32x4*)(cosT + (size_t)row * 16 + i0 + 4);
;                     const f32x4 s0 = *(const PG8_G f32x4*)(sinT + (size_t)row * 16 + i0), s1 = *(const PG8_G f32x4*)(sinT + (size_t)row * 16 + i0 + 4);
;                     const f32x4 x1a = acc[ai][0][m][0] * r[ai][m], x1b = acc[ai][0][m][1] * r[ai][m], x2a = acc[ai][1][m][0] * r[ai][m], x2b = acc[ai][1][m][1] * r[ai][m];
;                     const f32x4 y1a = x1a * c0 - x2a * s0, y1b = x1b * c1 - x2b * s1, y2a = x2a * c0 + x1a * s0, y2b = x2b * c1 + x1b * s1;
;                     bf16_t* dst = O + ((plane + hh * 4 + b) * 4096 + sp) * 128 + i0;
;                     *(PG8_G u32x4*)dst = pack8bf(y1a, y1b); *(PG8_G u32x4*)(dst + 16) = pack8bf(y2a, y2b); }
	v_pk_mul_f32 v[222:223], v[210:211], v[180:181]
	v_pk_mul_f32 v[224:225], v[212:213], v[178:179]
	s_waitcnt lgkmcnt(2)
	v_pk_mul_f32 v[232:233], v[214:215], v[184:185]
	v_pk_mul_f32 v[234:235], v[216:217], v[182:183]
	v_pk_mul_f32 v[180:181], v[196:197], v[180:181]
	v_pk_mul_f32 v[178:179], v[198:199], v[178:179]
	v_pk_mul_f32 v[184:185], v[206:207], v[184:185]
	v_pk_mul_f32 v[182:183], v[208:209], v[182:183]
	s_waitcnt lgkmcnt(1)
	v_pk_fma_f32 v[196:197], v[196:197], v[188:189], v[222:223] neg_lo:[0,0,1] neg_hi:[0,0,1]
	v_pk_fma_f32 v[198:199], v[198:199], v[186:187], v[224:225] neg_lo:[0,0,1] neg_hi:[0,0,1]
	s_waitcnt lgkmcnt(0)
	v_pk_fma_f32 v[206:207], v[206:207], v[192:193], v[232:233] neg_lo:[0,0,1] neg_hi:[0,0,1]
	v_pk_fma_f32 v[208:209], v[208:209], v[190:191], v[234:235] neg_lo:[0,0,1] neg_hi:[0,0,1]
	v_pk_fma_f32 v[188:189], v[210:211], v[188:189], v[180:181]
	v_pk_fma_f32 v[186:187], v[212:213], v[186:187], v[178:179]
	v_cvt_pk_bf16_f32 v178, v198, v199
	v_cvt_pk_bf16_f32 v179, v196, v197
	v_cvt_pk_bf16_f32 v180, v208, v209
	v_cvt_pk_bf16_f32 v181, v206, v207
	v_pk_fma_f32 v[184:185], v[214:215], v[192:193], v[184:185]
	v_pk_fma_f32 v[182:183], v[216:217], v[190:191], v[182:183]
	v_mov_b32_e32 v80, v178
	v_mov_b32_e32 v81, v179
	v_mov_b32_e32 v82, v180
	v_mov_b32_e32 v83, v181
	v_mov_b32_e32 v92, v220
	v_mov_b32_e32 v93, v221
	v_lshl_add_u64 v[190:191], v[146:147], 0, v[194:195]
	v_mov_b32_e32 v194, v163
	v_cvt_pk_bf16_f32 v178, v186, v187
	v_cvt_pk_bf16_f32 v179, v188, v189
	v_cvt_pk_bf16_f32 v180, v182, v183
	v_cvt_pk_bf16_f32 v181, v184, v185
	v_mov_b32_e32 v88, v178
	v_mov_b32_e32 v89, v179
	v_mov_b32_e32 v90, v180
	v_mov_b32_e32 v91, v181
	ds_read_b128 v[178:181], v240 offset:4096
	ds_read_b128 v[182:185], v240 offset:4608
	ds_read_b128 v[186:189], v240 offset:5120
	ds_read_b128 v[190:193], v240 offset:5632
	v_pk_mul_f32 v[172:173], v[86:87], v[194:195] op_sel_hi:[1,0]
	v_pk_mul_f32 v[196:197], v[84:85], v[194:195] op_sel_hi:[1,0]
	v_pk_mul_f32 v[198:199], v[78:79], v[194:195] op_sel_hi:[1,0]
	v_pk_mul_f32 v[206:207], v[76:77], v[194:195] op_sel_hi:[1,0]
	v_pk_mul_f32 v[208:209], v[74:75], v[194:195] op_sel_hi:[1,0]
	v_pk_mul_f32 v[210:211], v[72:73], v[194:195] op_sel_hi:[1,0]
	v_pk_mul_f32 v[212:213], v[70:71], v[194:195] op_sel_hi:[1,0]
	v_pk_mul_f32 v[194:195], v[68:69], v[194:195] op_sel_hi:[1,0]
	v_lshlrev_b64 v[214:215], 6, v[170:171]
	v_lshl_add_u64 v[216:217], v[148:149], 0, v[214:215]
	v_lshlrev_b32_e32 v170, s52, v170
	v_and_b32_e32 v169, 0xfff, v170
	v_add_lshl_u32 v200, v169, v167, 8
	v_lshl_add_u64 v[170:171], v[132:133], 0, v[200:201]
	s_waitcnt lgkmcnt(3)
	v_pk_mul_f32 v[218:219], v[208:209], v[180:181]
	v_pk_mul_f32 v[220:221], v[210:211], v[178:179]
	s_waitcnt lgkmcnt(2)
	v_pk_mul_f32 v[222:223], v[212:213], v[184:185]
	v_pk_mul_f32 v[224:225], v[194:195], v[182:183]
	v_pk_mul_f32 v[180:181], v[172:173], v[180:181]
	v_pk_mul_f32 v[178:179], v[196:197], v[178:179]
	v_pk_mul_f32 v[184:185], v[198:199], v[184:185]
	v_pk_mul_f32 v[182:183], v[206:207], v[182:183]
	s_waitcnt lgkmcnt(1)
	v_pk_fma_f32 v[172:173], v[172:173], v[188:189], v[218:219] neg_lo:[0,0,1] neg_hi:[0,0,1]
	v_pk_fma_f32 v[196:197], v[196:197], v[186:187], v[220:221] neg_lo:[0,0,1] neg_hi:[0,0,1]
	s_waitcnt lgkmcnt(0)
	v_pk_fma_f32 v[198:199], v[198:199], v[192:193], v[222:223] neg_lo:[0,0,1] neg_hi:[0,0,1]
	v_pk_fma_f32 v[206:207], v[206:207], v[190:191], v[224:225] neg_lo:[0,0,1] neg_hi:[0,0,1]
	v_pk_fma_f32 v[188:189], v[208:209], v[188:189], v[180:181]
	v_pk_fma_f32 v[186:187], v[210:211], v[186:187], v[178:179]
	v_cvt_pk_bf16_f32 v178, v196, v197
	v_cvt_pk_bf16_f32 v179, v172, v173
	v_cvt_pk_bf16_f32 v180, v206, v207
	v_cvt_pk_bf16_f32 v181, v198, v199
	v_pk_fma_f32 v[184:185], v[212:213], v[192:193], v[184:185]
	v_pk_fma_f32 v[182:183], v[194:195], v[190:191], v[182:183]
	v_mov_b32_e32 v68, v178
	v_mov_b32_e32 v69, v179
	v_mov_b32_e32 v70, v180
	v_mov_b32_e32 v71, v181
	v_mov_b32_e32 v76, v134
	v_mov_b32_e32 v77, v135
	v_pk_mul_f32 v[206:207], v[58:59], v[160:161] op_sel_hi:[1,0]
	v_pk_mul_f32 v[208:209], v[56:57], v[160:161] op_sel_hi:[1,0]
	v_cvt_pk_bf16_f32 v178, v186, v187
	v_cvt_pk_bf16_f32 v179, v188, v189
	v_cvt_pk_bf16_f32 v180, v182, v183
	v_cvt_pk_bf16_f32 v181, v184, v185
	v_mov_b32_e32 v72, v178
	v_mov_b32_e32 v73, v179
	v_mov_b32_e32 v74, v180
	v_mov_b32_e32 v75, v181
	ds_read_b128 v[178:181], v240 offset:6144
	ds_read_b128 v[182:185], v240 offset:6656
	ds_read_b128 v[186:189], v240 offset:7168
	ds_read_b128 v[190:193], v240 offset:7680
	v_lshl_add_u64 v[134:135], v[146:147], 0, v[214:215]
	v_add_u32_e32 v134, 0x90, v166
	v_pk_mul_f32 v[172:173], v[66:67], v[160:161] op_sel_hi:[1,0]
	v_pk_mul_f32 v[194:195], v[64:65], v[160:161] op_sel_hi:[1,0]
	v_pk_mul_f32 v[210:211], v[50:51], v[160:161] op_sel_hi:[1,0]
	v_pk_mul_f32 v[212:213], v[48:49], v[160:161] op_sel_hi:[1,0]
	v_lshl_add_u64 v[218:219], v[170:171], 0, v[154:155]
	v_pk_mul_f32 v[196:197], v[62:63], v[160:161] op_sel_hi:[1,0]
	v_pk_mul_f32 v[198:199], v[60:61], v[160:161] op_sel_hi:[1,0]
	v_ashrrev_i32_e32 v135, 31, v134
	v_lshlrev_b64 v[214:215], 6, v[134:135]
	v_lshl_add_u64 v[216:217], v[148:149], 0, v[214:215]
	v_lshlrev_b32_e32 v167, s52, v134
	v_and_b32_e32 v169, 0xfdf, v134
	v_and_b32_e32 v167, 0xfff, v167
	v_lshrrev_b32_e32 v169, s44, v169
	v_add_lshl_u32 v200, v167, v169, 8
	s_waitcnt lgkmcnt(3)
	v_pk_mul_f32 v[170:171], v[206:207], v[180:181]
	v_pk_mul_f32 v[220:221], v[208:209], v[178:179]
	s_waitcnt lgkmcnt(2)
	v_pk_mul_f32 v[222:223], v[210:211], v[184:185]
	v_pk_mul_f32 v[224:225], v[212:213], v[182:183]
	v_pk_mul_f32 v[180:181], v[172:173], v[180:181]
	s_waitcnt lgkmcnt(1)
; #define PG8_G __attribute__((address_space(1)))
; __device__ __forceinline__ u32x4 pack8bf(const f32x4 a, const f32x4 b) { u32x4 w; w.x = cvt_pk_bf16(a[0], a[1]); w.y = cvt_pk_bf16(a[2], a[3]); w.z = cvt_pk_bf16(b[0], b[1]); w.w = cvt_pk_bf16(b[2], b[3]); return w; }
;     __device__ __forceinline__ void operator()(const f32x4 (&acc)[2][2][4][2], const Unit& u, int wr, int wc, int fr, int fq, int ui) const {
;     ...
;             const int hh = fq >> 1, i0 = 8 * (fq & 1);
; #pragma unroll
;             for (int ai = 0; ai < 2; ++ai)
; #pragma unroll
;                 for (int m = 0; m < 4; ++m) { const int row = row0 + ai * HALF + m * 16, b = row >> 12, s = row & 4095, sp = ((s & ((1 << sh) - 1)) << (12 - sh)) + (s >> sh);
;                     const f32x4 c0 = *(const PG8_G f32x4*)(cosT + (size_t)row * 16 + i0), c1 = *(const PG8_G f32x4*)(cosT + (size_t)row * 16 + i0 + 4);
;                     const f32x4 s0 = *(const PG8_G f32x4*)(sinT + (size_t)row * 16 + i0), s1 = *(const PG8_G f32x4*)(sinT + (size_t)row * 16 + i0 + 4);
;                     const f32x4 x1a = acc[ai][0][m][0] * r[ai][m], x1b = acc[ai][0][m][1] * r[ai][m], x2a = acc[ai][1][m][0] * r[ai][m], x2b = acc[ai][1][m][1] * r[ai][m];
;                     const f32x4 y1a = x1a * c0 - x2a * s0, y1b = x1b * c1 - x2b * s1, y2a = x2a * c0 + x1a * s0, y2b = x2b * c1 + x1b * s1;
;                     bf16_t* dst = O + ((plane + hh * 4 + b) * 4096 + sp) * 128 + i0;
;                     *(PG8_G u32x4*)dst = pack8bf(y1a, y1b); *(PG8_G u32x4*)(dst + 16) = pack8bf(y2a, y2b); }
	v_pk_fma_f32 v[172:173], v[172:173], v[188:189], v[170:171] neg_lo:[0,0,1] neg_hi:[0,0,1]
	v_pk_fma_f32 v[170:171], v[194:195], v[186:187], v[220:221] neg_lo:[0,0,1] neg_hi:[0,0,1]
	v_pk_mul_f32 v[178:179], v[194:195], v[178:179]
	v_pk_mul_f32 v[184:185], v[196:197], v[184:185]
	v_pk_mul_f32 v[182:183], v[198:199], v[182:183]
	s_waitcnt lgkmcnt(0)
	v_pk_fma_f32 v[194:195], v[196:197], v[192:193], v[222:223] neg_lo:[0,0,1] neg_hi:[0,0,1]
	v_pk_fma_f32 v[196:197], v[198:199], v[190:191], v[224:225] neg_lo:[0,0,1] neg_hi:[0,0,1]
	v_cvt_pk_bf16_f32 v170, v170, v171
	v_cvt_pk_bf16_f32 v171, v172, v173
	v_pk_fma_f32 v[180:181], v[206:207], v[188:189], v[180:181]
	v_cvt_pk_bf16_f32 v172, v196, v197
	v_cvt_pk_bf16_f32 v173, v194, v195
	v_pk_fma_f32 v[178:179], v[208:209], v[186:187], v[178:179]
	v_pk_fma_f32 v[184:185], v[210:211], v[192:193], v[184:185]
	v_pk_fma_f32 v[182:183], v[212:213], v[190:191], v[182:183]
	v_mov_b32_e32 v48, v170
	v_mov_b32_e32 v49, v171
	v_mov_b32_e32 v50, v172
	v_mov_b32_e32 v51, v173
	v_mov_b32_e32 v60, v218
	v_mov_b32_e32 v61, v219
	v_lshl_add_u64 v[186:187], v[146:147], 0, v[214:215]
	v_mov_b32_e32 v192, v161
	v_cvt_pk_bf16_f32 v170, v178, v179
	v_cvt_pk_bf16_f32 v171, v180, v181
	v_cvt_pk_bf16_f32 v172, v182, v183
	v_cvt_pk_bf16_f32 v173, v184, v185
	v_mov_b32_e32 v56, v170
	v_mov_b32_e32 v57, v171
	v_mov_b32_e32 v58, v172
	v_mov_b32_e32 v59, v173
	ds_read_b128 v[170:173], v240 offset:8192
	ds_read_b128 v[178:181], v240 offset:8704
	ds_read_b128 v[182:185], v240 offset:9216
	ds_read_b128 v[186:189], v240 offset:9728
	v_add_u32_e32 v190, 0xa0, v166
	v_pk_mul_f32 v[134:135], v[54:55], v[192:193] op_sel_hi:[1,0]
	v_pk_mul_f32 v[194:195], v[52:53], v[192:193] op_sel_hi:[1,0]
	v_pk_mul_f32 v[196:197], v[46:47], v[192:193] op_sel_hi:[1,0]
	v_pk_mul_f32 v[198:199], v[44:45], v[192:193] op_sel_hi:[1,0]
	v_pk_mul_f32 v[206:207], v[42:43], v[192:193] op_sel_hi:[1,0]
	v_pk_mul_f32 v[208:209], v[40:41], v[192:193] op_sel_hi:[1,0]
	v_pk_mul_f32 v[210:211], v[34:35], v[192:193] op_sel_hi:[1,0]
	v_pk_mul_f32 v[192:193], v[32:33], v[192:193] op_sel_hi:[1,0]
	v_ashrrev_i32_e32 v191, 31, v190
	v_lshl_add_u64 v[216:217], v[132:133], 0, v[200:201]
	v_lshlrev_b64 v[212:213], 6, v[190:191]
	v_lshl_add_u64 v[216:217], v[216:217], 0, v[154:155]
	v_lshl_add_u64 v[214:215], v[148:149], 0, v[212:213]
	v_lshlrev_b32_e32 v167, s52, v190
	v_and_b32_e32 v169, 0xfef, v190
	v_and_b32_e32 v167, 0xfff, v167
	v_lshrrev_b32_e32 v169, s44, v169
	v_add_lshl_u32 v200, v167, v169, 8
	s_waitcnt lgkmcnt(3)
	v_pk_mul_f32 v[218:219], v[206:207], v[172:173]
	v_pk_mul_f32 v[220:221], v[208:209], v[170:171]
	s_waitcnt lgkmcnt(2)
	v_pk_mul_f32 v[222:223], v[210:211], v[180:181]
	v_pk_mul_f32 v[224:225], v[192:193], v[178:179]
	v_pk_mul_f32 v[172:173], v[134:135], v[172:173]
	v_pk_mul_f32 v[170:171], v[194:195], v[170:171]
	v_pk_mul_f32 v[180:181], v[196:197], v[180:181]
	v_pk_mul_f32 v[178:179], v[198:199], v[178:179]
	s_waitcnt lgkmcnt(1)
	v_pk_fma_f32 v[134:135], v[134:135], v[184:185], v[218:219] neg_lo:[0,0,1] neg_hi:[0,0,1]
	v_pk_fma_f32 v[194:195], v[194:195], v[182:183], v[220:221] neg_lo:[0,0,1] neg_hi:[0,0,1]
	s_waitcnt lgkmcnt(0)
	v_pk_fma_f32 v[196:197], v[196:197], v[188:189], v[222:223] neg_lo:[0,0,1] neg_hi:[0,0,1]
	v_pk_fma_f32 v[198:199], v[198:199], v[186:187], v[224:225] neg_lo:[0,0,1] neg_hi:[0,0,1]
	v_pk_fma_f32 v[184:185], v[206:207], v[184:185], v[172:173]
	v_pk_fma_f32 v[182:183], v[208:209], v[182:183], v[170:171]
	v_cvt_pk_bf16_f32 v170, v194, v195
	v_cvt_pk_bf16_f32 v171, v134, v135
	v_cvt_pk_bf16_f32 v172, v198, v199
	v_cvt_pk_bf16_f32 v173, v196, v197
	v_pk_fma_f32 v[180:181], v[210:211], v[188:189], v[180:181]
	v_pk_fma_f32 v[178:179], v[192:193], v[186:187], v[178:179]
	v_mov_b32_e32 v32, v170
	v_mov_b32_e32 v33, v171
	v_mov_b32_e32 v34, v172
	v_mov_b32_e32 v35, v173
	v_mov_b32_e32 v44, v216
	v_mov_b32_e32 v45, v217
	v_lshl_add_u64 v[134:135], v[146:147], 0, v[212:213]
	v_pk_mul_f32 v[192:193], v[38:39], v[158:159] op_sel_hi:[1,0]
	v_cvt_pk_bf16_f32 v170, v182, v183
	v_cvt_pk_bf16_f32 v171, v184, v185
	v_cvt_pk_bf16_f32 v172, v178, v179
	v_cvt_pk_bf16_f32 v173, v180, v181
	v_mov_b32_e32 v40, v170
	v_mov_b32_e32 v41, v171
	v_mov_b32_e32 v42, v172
	v_mov_b32_e32 v43, v173
	ds_read_b128 v[170:173], v240 offset:10240
	ds_read_b128 v[178:181], v240 offset:10752
	ds_read_b128 v[182:185], v240 offset:11264
	ds_read_b128 v[186:189], v240 offset:11776
	v_add_u32_e32 v134, 0xb0, v166
	v_pk_mul_f32 v[194:195], v[36:37], v[158:159] op_sel_hi:[1,0]
	v_pk_mul_f32 v[206:207], v[26:27], v[158:159] op_sel_hi:[1,0]
	v_pk_mul_f32 v[208:209], v[24:25], v[158:159] op_sel_hi:[1,0]
	v_pk_mul_f32 v[210:211], v[18:19], v[158:159] op_sel_hi:[1,0]
	v_pk_mul_f32 v[212:213], v[16:17], v[158:159] op_sel_hi:[1,0]
	v_pk_mul_f32 v[196:197], v[30:31], v[158:159] op_sel_hi:[1,0]
	v_pk_mul_f32 v[198:199], v[28:29], v[158:159] op_sel_hi:[1,0]
	v_ashrrev_i32_e32 v135, 31, v134
	v_lshl_add_u64 v[216:217], v[132:133], 0, v[200:201]
	v_lshlrev_b64 v[190:191], 6, v[134:135]
	v_lshl_add_u64 v[216:217], v[216:217], 0, v[154:155]
	v_lshl_add_u64 v[214:215], v[148:149], 0, v[190:191]
	v_lshlrev_b32_e32 v167, s52, v134
	v_and_b32_e32 v169, 0xfff, v134
	v_and_b32_e32 v167, 0xfff, v167
	v_lshrrev_b32_e32 v169, s44, v169
	v_add_lshl_u32 v200, v167, v169, 8
	v_lshl_add_u64 v[132:133], v[132:133], 0, v[200:201]
	s_waitcnt lgkmcnt(3)
; #define PG8_G __attribute__((address_space(1)))
; __device__ __forceinline__ u32x4 pack8bf(const f32x4 a, const f32x4 b) { u32x4 w; w.x = cvt_pk_bf16(a[0], a[1]); w.y = cvt_pk_bf16(a[2], a[3]); w.z = cvt_pk_bf16(b[0], b[1]); w.w = cvt_pk_bf16(b[2], b[3]); return w; }
;     __device__ __forceinline__ void operator()(const f32x4 (&acc)[2][2][4][2], const Unit& u, int wr, int wc, int fr, int fq, int ui) const {
;     ...
;             const int hh = fq >> 1, i0 = 8 * (fq & 1);
; #pragma unroll
;             for (int ai = 0; ai < 2; ++ai)
; #pragma unroll
;                 for (int m = 0; m < 4; ++m) { const int row = row0 + ai * HALF + m * 16, b = row >> 12, s = row & 4095, sp = ((s & ((1 << sh) - 1)) << (12 - sh)) + (s >> sh);
;                     const f32x4 c0 = *(const PG8_G f32x4*)(cosT + (size_t)row * 16 + i0), c1 = *(const PG8_G f32x4*)(cosT + (size_t)row * 16 + i0 + 4);
;                     const f32x4 s0 = *(const PG8_G f32x4*)(sinT + (size_t)row * 16 + i0), s1 = *(const PG8_G f32x4*)(sinT + (size_t)row * 16 + i0 + 4);
;                     const f32x4 x1a = acc[ai][0][m][0] * r[ai][m], x1b = acc[ai][0][m][1] * r[ai][m], x2a = acc[ai][1][m][0] * r[ai][m], x2b = acc[ai][1][m][1] * r[ai][m];
;                     const f32x4 y1a = x1a * c0 - x2a * s0, y1b = x1b * c1 - x2b * s1, y2a = x2a * c0 + x1a * s0, y2b = x2b * c1 + x1b * s1;
;                     bf16_t* dst = O + ((plane + hh * 4 + b) * 4096 + sp) * 128 + i0;
;                     *(PG8_G u32x4*)dst = pack8bf(y1a, y1b); *(PG8_G u32x4*)(dst + 16) = pack8bf(y2a, y2b); }
	v_pk_mul_f32 v[218:219], v[206:207], v[172:173]
	v_pk_mul_f32 v[220:221], v[208:209], v[170:171]
	s_waitcnt lgkmcnt(2)
	v_pk_mul_f32 v[222:223], v[210:211], v[180:181]
	v_pk_mul_f32 v[224:225], v[212:213], v[178:179]
	v_pk_mul_f32 v[172:173], v[192:193], v[172:173]
	v_pk_mul_f32 v[170:171], v[194:195], v[170:171]
	v_pk_mul_f32 v[180:181], v[196:197], v[180:181]
	v_pk_mul_f32 v[178:179], v[198:199], v[178:179]
	s_waitcnt lgkmcnt(1)
	v_pk_fma_f32 v[192:193], v[192:193], v[184:185], v[218:219] neg_lo:[0,0,1] neg_hi:[0,0,1]
	v_pk_fma_f32 v[194:195], v[194:195], v[182:183], v[220:221] neg_lo:[0,0,1] neg_hi:[0,0,1]
	s_waitcnt lgkmcnt(0)
	v_pk_fma_f32 v[196:197], v[196:197], v[188:189], v[222:223] neg_lo:[0,0,1] neg_hi:[0,0,1]
	v_pk_fma_f32 v[198:199], v[198:199], v[186:187], v[224:225] neg_lo:[0,0,1] neg_hi:[0,0,1]
	v_pk_fma_f32 v[184:185], v[206:207], v[184:185], v[172:173]
	v_pk_fma_f32 v[182:183], v[208:209], v[182:183], v[170:171]
	v_cvt_pk_bf16_f32 v170, v194, v195
	v_cvt_pk_bf16_f32 v171, v192, v193
	v_cvt_pk_bf16_f32 v172, v198, v199
	v_cvt_pk_bf16_f32 v173, v196, v197
	v_pk_fma_f32 v[180:181], v[210:211], v[188:189], v[180:181]
	v_pk_fma_f32 v[178:179], v[212:213], v[186:187], v[178:179]
	v_mov_b32_e32 v16, v170
	v_mov_b32_e32 v17, v171
	v_mov_b32_e32 v18, v172
	v_mov_b32_e32 v19, v173
	v_mov_b32_e32 v28, v216
	v_mov_b32_e32 v29, v217
	v_lshl_add_u64 v[212:213], v[132:133], 0, v[154:155]
	s_nop 0
	v_cvt_pk_bf16_f32 v170, v182, v183
	v_cvt_pk_bf16_f32 v171, v184, v185
	v_cvt_pk_bf16_f32 v172, v178, v179
	v_cvt_pk_bf16_f32 v173, v180, v181
	v_mov_b32_e32 v24, v170
	v_mov_b32_e32 v25, v171
	v_mov_b32_e32 v26, v172
	v_mov_b32_e32 v27, v173
	ds_read_b128 v[178:181], v240 offset:12288
	ds_read_b128 v[182:185], v240 offset:12800
	ds_read_b128 v[186:189], v240 offset:13312
	ds_read_b128 v[190:193], v240 offset:13824
	v_lshl_add_u64 v[170:171], v[146:147], 0, v[190:191]
	v_mov_b32_e32 v170, v159
	v_pk_mul_f32 v[206:207], v[10:11], v[170:171] op_sel_hi:[1,0]
	v_pk_mul_f32 v[208:209], v[8:9], v[170:171] op_sel_hi:[1,0]
	v_pk_mul_f32 v[134:135], v[22:23], v[170:171] op_sel_hi:[1,0]
	v_pk_mul_f32 v[194:195], v[20:21], v[170:171] op_sel_hi:[1,0]
	v_pk_mul_f32 v[196:197], v[14:15], v[170:171] op_sel_hi:[1,0]
	v_pk_mul_f32 v[198:199], v[12:13], v[170:171] op_sel_hi:[1,0]
	v_pk_mul_f32 v[210:211], v[6:7], v[170:171] op_sel_hi:[1,0]
	v_pk_mul_f32 v[170:171], v[4:5], v[170:171] op_sel_hi:[1,0]
	v_lshl_add_u64 v[172:173], v[212:213], 0, 32
	s_waitcnt lgkmcnt(3)
	v_pk_mul_f32 v[132:133], v[206:207], v[180:181]
	v_pk_mul_f32 v[214:215], v[208:209], v[178:179]
	s_waitcnt lgkmcnt(2)
	v_pk_mul_f32 v[216:217], v[210:211], v[184:185]
	v_pk_mul_f32 v[218:219], v[170:171], v[182:183]
	v_pk_mul_f32 v[180:181], v[134:135], v[180:181]
	s_waitcnt lgkmcnt(1)
	v_pk_fma_f32 v[134:135], v[134:135], v[188:189], v[132:133] neg_lo:[0,0,1] neg_hi:[0,0,1]
	v_pk_fma_f32 v[132:133], v[194:195], v[186:187], v[214:215] neg_lo:[0,0,1] neg_hi:[0,0,1]
	v_pk_mul_f32 v[178:179], v[194:195], v[178:179]
	v_pk_mul_f32 v[184:185], v[196:197], v[184:185]
	v_pk_mul_f32 v[182:183], v[198:199], v[182:183]
	s_waitcnt lgkmcnt(0)
	v_pk_fma_f32 v[194:195], v[196:197], v[192:193], v[216:217] neg_lo:[0,0,1] neg_hi:[0,0,1]
	v_pk_fma_f32 v[196:197], v[198:199], v[190:191], v[218:219] neg_lo:[0,0,1] neg_hi:[0,0,1]
	v_cvt_pk_bf16_f32 v132, v132, v133
	v_cvt_pk_bf16_f32 v133, v134, v135
	v_pk_fma_f32 v[180:181], v[206:207], v[188:189], v[180:181]
	v_cvt_pk_bf16_f32 v134, v196, v197
	v_cvt_pk_bf16_f32 v135, v194, v195
	v_pk_fma_f32 v[178:179], v[208:209], v[186:187], v[178:179]
	v_pk_fma_f32 v[184:185], v[210:211], v[192:193], v[184:185]
	v_pk_fma_f32 v[170:171], v[170:171], v[190:191], v[182:183]
	global_store_dwordx4 v[212:213], v[132:135], off
	s_nop 1
	v_cvt_pk_bf16_f32 v132, v178, v179
	v_cvt_pk_bf16_f32 v133, v180, v181
	v_cvt_pk_bf16_f32 v134, v170, v171
	v_cvt_pk_bf16_f32 v135, v184, v185
	global_store_dwordx4 v[124:125], v[112:115], off
	global_store_dwordx4 v[124:125], v[120:123], off offset:32
	global_store_dwordx4 v[108:109], v[96:99], off
	global_store_dwordx4 v[108:109], v[104:107], off offset:32
	global_store_dwordx4 v[92:93], v[80:83], off
	global_store_dwordx4 v[92:93], v[88:91], off offset:32
	global_store_dwordx4 v[76:77], v[68:71], off
	global_store_dwordx4 v[76:77], v[72:75], off offset:32
	global_store_dwordx4 v[60:61], v[48:51], off
	global_store_dwordx4 v[60:61], v[56:59], off offset:32
	global_store_dwordx4 v[44:45], v[32:35], off
	global_store_dwordx4 v[44:45], v[40:43], off offset:32
	global_store_dwordx4 v[28:29], v[16:19], off
	global_store_dwordx4 v[28:29], v[24:27], off offset:32
	s_cbranch_execnz .LBB0_758
